# baseline (speedup 1.0000x reference)
; __device__ __forceinline__ int otid() { int t = threadIdx.x; asm volatile("" : "+v"(t)); return t; }
; __device__ __forceinline__ void ph_indexer(const Params& p, char* shm) {
;   const int tid = otid(), wid = __builtin_amdgcn_readfirstlane(tid >> 6), lane = tid & 63, col = lane & 31, half = lane >> 5;
;   char* wtab = shm + 65536;
;   for (int item = blockIdx.x; item < 512; item += gridDim.x) {
;     const int b = item >> 8, cp = item & 255;
;     for (int side = 0; side < 2; ++side) {
;       const int chunk = side ? 511 - cp : cp;
;       const int t0 = chunk * 16, nst = (t0 + 16 + 127) >> 7;
;       const size_t rowb = (size_t)b * L + t0;
;       const u16* kib = p.KI + (size_t)b * L * 128;
;       s16x8 Aq[2][8];
; #pragma unroll
;       for (int q = 0; q < 2; ++q) {
;         const u16* qp = p.P + (rowb + wid * 2 + q) * NP + QI_OFF + col * 128 + half * 8;
; __global__ void __launch_bounds__(512, 2) mega(Params p, int ph0, int ph1) {
;     ...
;       switch (s) {
;         case 0: ph_proj(p, l, shm); break;
;         case 1: ph_post(p, l, shm); break;
;         case 2:
;           for (int r2 = 0; r2 < (((REPMASK >> 9) & 1u) ? 2 : 1); ++r2) { ph_indexer(p, shm); __syncthreads(); }
.LBB0_911:
	s_andn2_b64 vcc, exec, s[0:1]
	s_cbranch_vccnz .LBB0_1745
	v_readlane_b32 s0, v245, 53
	s_cmp_lt_i32 s0, 2
	s_mov_b64 s[0:1], -1
	s_cbranch_scc1 .LBB0_954
	v_readlane_b32 s0, v245, 53
	s_cmp_lt_i32 s0, 3
	s_cbranch_scc0 .LBB0_953
	v_readlane_b32 s0, v246, 30
	v_mov_b32_e32 v0, v204
	v_readlane_b32 s1, v246, 31
	s_andn2_b64 vcc, exec, s[0:1]
	v_readfirstlane_b32 s2, v0
	s_cbranch_vccnz .LBB0_947
	s_ashr_i32 s3, s2, 6
	s_cmp_ge_u32 s3, 4
	s_cbranch_scc0 .Lidx_prio_done
	s_setprio 1
.Lidx_prio_done:
	s_lshl_b32 s4, s3, 2
	v_and_b32_e32 v3, 31, v0
	s_ashr_i32 s2, s2, 7
	s_and_b32 s4, s4, 4
	v_lshl_or_b32 v118, s2, 5, v3
	s_lshl_b32 s26, s2, 13
	s_or_b32 s2, s4, 1
	v_and_b32_e32 v2, 63, v0
	v_lshrrev_b32_e32 v1, 2, v0
	s_lshl_b32 s30, s2, 4
	s_lshl_b32 s31, s2, 10
	s_or_b32 s2, s4, 2
	v_readlane_b32 s8, v246, 0
	s_lshl_b32 s24, s3, 1
	v_and_b32_e32 v116, 8, v1
	s_movk_i32 s0, 0x100
	v_ashrrev_i32_e32 v1, 31, v0
	v_ashrrev_i32_e32 v119, 31, v118
	s_lshl_b32 s27, s3, 7
	s_lshl_b32 s34, s2, 4
	s_lshl_b32 s35, s2, 10
	s_or_b32 s2, s4, 3
	v_readlane_b32 s9, v246, 1
	v_readlane_b32 s10, v246, 2
	v_readlane_b32 s11, v246, 3
	v_lshlrev_b32_e32 v32, 2, v2
	s_ashr_i32 s25, s24, 31
	v_lshlrev_b32_e32 v114, 7, v3
	v_cmp_gt_i32_e64 s[0:1], s0, v0
	v_lshl_add_u32 v115, v0, 2, v217
	v_lshlrev_b64 v[120:121], 8, v[118:119]
	s_add_i32 s27, s27, 0x10000
	v_lshlrev_b32_e32 v117, 4, v2
	v_cmp_gt_u32_e64 s[6:7], 32, v2
	s_lshl_b32 s28, s4, 4
	s_lshl_b32 s29, s4, 10
	s_lshl_b32 s36, s2, 4
	s_lshl_b32 s37, s2, 10
	v_lshl_add_u64 v[122:123], v[0:1], 3, s[8:9]
	v_lshl_add_u64 v[124:125], s[10:11], 0, v[32:33]
	v_lshlrev_b32_e32 v32, 1, v116
	v_and_b32_e32 v114, 15, v204
	v_and_b32_e32 v117, 48, v204
	v_lshlrev_b32_e32 v114, 7, v114
	v_lshrrev_b32_e32 v0, 1, v117
	v_or_b32_e32 v114, v114, v0
	v_and_b32_e32 v0, 15, v204
	v_lshlrev_b32_e32 v0, 4, v0
	v_lshl_or_b32 v117, v117, 5, v0
	s_mov_b32 s38, s86
	s_branch .LBB0_917

; __device__ __forceinline__ int otid() { int t = threadIdx.x; asm volatile("" : "+v"(t)); return t; }
; __device__ __forceinline__ void ph_gmlp(const Params& p, int l, char* shm) {
;   const int tid = otid(), wid = __builtin_amdgcn_readfirstlane(tid >> 6), lane = tid & 63, m = lane & 15, g4 = lane >> 4;
;   for (int tile = blockIdx.x; tile < 2048; tile += gridDim.x) {
;     const int g = tile & 15, ch = tile >> 4;
;     const size_t tok0 = (size_t)ch * 128;
;     const int i = wid * 16 + m;
;     const size_t t = tok0 + i;
;     uint2 uu[8], gg[8];
;     {
;       const u16* up = p.P + t * NP + U_OFF + g * 128 + g4 * 4;
;       const u16* gp = p.P + t * NP + GB_OFF + g * 128 + g4 * 4;
; #pragma unroll
;       for (int nt = 0; nt < 8; ++nt) { uu[nt] = *(const uint2*)(up + nt * 16); gg[nt] = *(const uint2*)(gp + nt * 16); }
;     }
;     const float bias = p.b_s[(l * 16 + g) * 128 + i];
;     {
;       const int r = tid >> 2, q = tid & 3;
;       const uint4* src = (const uint4*)(p.P + (tok0 + r) * NP + V_OFF + g * 128 + q * 32);
; #pragma unroll
;       for (int k = 0; k < 4; ++k) *(uint4*)(shm + r * 272 + q * 64 + k * 16) = src[k];
;     }
;     __syncthreads();
;     f32x4 acc[8];
; #pragma unroll
;     for (int nt = 0; nt < 8; ++nt) acc[nt] = f32x4{0.f, 0.f, 0.f, 0.f};
;     const u16* wsb = p.ws + ((size_t)(l * 16 + g) * 128 + wid * 16 + m) * 128 + g4 * 4;
;     const int rdbase = (g4 * 4 + (m >> 2)) * 272 + (m & 3) * 8;
; __global__ void __launch_bounds__(512, 2) mega(Params p, int ph0, int ph1) {
;     ...
;           for (int r2 = 0; r2 < (((REPMASK >> 9) & 1u) ? 2 : 1); ++r2) { ph_indexer(p, shm); __syncthreads(); }
;           for (int r2 = 0; r2 < (((REPMASK >> 10) & 1u) ? 2 : 1); ++r2) { ph_gmlp(p, l, shm); }
.LBB0_947:
	s_setprio 0
	v_readlane_b32 s0, v246, 32
	v_mov_b32_e32 v0, v204
	v_readlane_b32 s1, v246, 33
	v_readlane_b32 s16, v245, 25
	s_waitcnt vmcnt(0)
	s_barrier
	s_andn2_b64 vcc, exec, s[0:1]
	v_readfirstlane_b32 s0, v0
	v_readlane_b32 s17, v245, 26
	v_readlane_b32 s18, v245, 27
	v_readlane_b32 s19, v245, 28
	v_readlane_b32 s20, v245, 29
	v_readlane_b32 s21, v245, 30
	v_readlane_b32 s22, v245, 31
	v_readlane_b32 s23, v245, 32
	v_readlane_b32 s24, v245, 33
	v_readlane_b32 s25, v245, 34
	v_readlane_b32 s26, v245, 35
	v_readlane_b32 s27, v245, 36
	v_readlane_b32 s28, v245, 37
	v_readlane_b32 s29, v245, 38
	v_readlane_b32 s30, v245, 39
	v_readlane_b32 s31, v245, 40
	v_readlane_b32 s14, v245, 48
	s_cbranch_vccnz .LBB0_953
	s_ashr_i32 s7, s0, 6
	v_readlane_b32 s2, v245, 49
	v_and_b32_e32 v1, 15, v0
	s_lshl_b32 s0, s7, 4
	s_lshl_b32 s6, s2, 4
	v_or_b32_e32 v34, s0, v1
	v_lshrrev_b32_e32 v1, 2, v0
	v_ashrrev_i32_e32 v36, 2, v0
	s_movk_i32 s1, 0x110
	s_ashr_i32 s2, s0, 31
	v_and_b32_e32 v2, 12, v1
	v_and_b32_e32 v1, 3, v0
	v_mul_lo_u32 v3, v36, s1
	v_mov_b32_e32 v7, s2
	v_mov_b32_e32 v6, v34
	v_readlane_b32 s3, v245, 50
	v_lshlrev_b32_e32 v4, 5, v1
	v_lshl_add_u32 v47, v1, 6, v3
	v_bfe_u32 v1, v0, 2, 4
	v_lshlrev_b32_e32 v3, 3, v0
	v_lshlrev_b64 v[6:7], 8, v[6:7]
	v_lshrrev_b32_e32 v0, 1, v0
	v_mul_u32_u24_e32 v1, 0x110, v1
	v_and_b32_e32 v3, 24, v3
	s_cmp_gt_i32 s7, -1
	s_movk_i32 s3, 0xe0
	v_and_or_b32 v6, v0, 24, v6
	v_ashrrev_i32_e32 v35, 31, v34
	v_ashrrev_i32_e32 v37, 31, v36
	s_cselect_b64 s[0:1], -1, 0
	v_add_u32_e32 v80, 16, v47
	v_add_u32_e32 v81, 32, v47
	v_add_u32_e32 v82, 48, v47
	s_add_i32 s7, s7, 1
	v_add3_u32 v83, v1, v3, s3
	v_lshl_add_u64 v[38:39], s[22:23], 0, v[6:7]
	v_lshlrev_b32_e32 v40, 1, v4
	v_lshlrev_b32_e32 v32, 1, v2
	s_mov_b32 s8, s86
	s_mov_b32 s9, s86
	s_branch .LBB0_950
